# FFN-down epilogues: lane^32 stage of the row sum-of-squares reduction done with v_permlane32_swap instead of an ds_bpermute LDS round trip (strategy lever 7: intra-wave movement without LDS)
# baseline (speedup 1.0000x reference)
; __device__ __forceinline__ float sq4(f32x4 a) { return (a.x * a.x + a.y * a.y) + (a.z * a.z + a.w * a.w); }
; __device__ __forceinline__ u32x4 pack8(f32x4 a, f32x4 b) { u32x4 o; o.x = cvt_pk(a.x, a.y); o.y = cvt_pk(a.z, a.w); o.z = cvt_pk(b.x, b.y); o.w = cvt_pk(b.z, b.w); return o; }
; __device__ __forceinline__ void row_stat_add(float* SS, int row, float v, int fq) {
;     v += __shfl_xor(v, 16); v += __shfl_xor(v, 32);
;     if (fq == 0) unsafeAtomicAdd(SS + row, v);
;     __device__ __forceinline__ void operator()(const f32x4 (&acc)[2][2][4][2], const pg8::Unit& u, int wr, int wc, int fr, int fq) const {
;     ...
;         for (int ai = 0; ai < 2; ++ai)
; #pragma unroll
;             for (int m = 0; m < 4; ++m) {
;                 const int row = row0 + ai * 128 + m * 16; float ssq = 0.f;
; #pragma unroll
;                 for (int bj = 0; bj < 2; ++bj) {
;                     const size_t idx = (size_t)row * D + col0 + bj * 128;
;                     f32x4 r0, r1;
;                     if (RF32) { r0 = *(const f32x4*)(R + idx); r1 = *(const f32x4*)(R + idx + 4); }
;                     else { const u32x4 w = *(const u32x4*)(X + idx); r0 = (f32x4){bflo(w.x), bfhi(w.x), bflo(w.y), bfhi(w.y)}; r1 = (f32x4){bflo(w.z), bfhi(w.z), bflo(w.w), bfhi(w.w)}; }
;                     const f32x4 v0 = r0 + acc[ai][bj][m][0] * s, v1 = r1 + acc[ai][bj][m][1] * s;
;                     ssq += sq4(v0) + sq4(v1);
;                     *(u32x4*)(X + idx) = pack8(v0, v1);
;                 }
;                 row_stat_add(SS, row, ssq, fq);
.LBB0_259:
	v_lshl_add_u32 v146, s67, 8, v148
	v_lshl_or_b32 v144, s66, 8, v150
	v_ashrrev_i32_e32 v147, 31, v146
	v_ashrrev_i32_e32 v145, 31, v144
	v_lshlrev_b64 v[156:157], 10, v[146:147]
	v_lshl_add_u64 v[164:165], v[156:157], 0, v[144:145]
	v_lshl_add_u64 v[168:169], v[164:165], 2, s[12:13]
	global_load_dwordx4 v[156:159], v[168:169], off offset:16
	global_load_dwordx4 v[160:163], v[168:169], off
	s_waitcnt vmcnt(0)
	v_pk_fma_f32 v[158:159], v[122:123], 0.5, v[158:159] op_sel_hi:[1,0,1]
	v_pk_fma_f32 v[126:127], v[126:127], 0.5, v[162:163] op_sel_hi:[1,0,1]
	v_pk_fma_f32 v[124:125], v[124:125], 0.5, v[160:161] op_sel_hi:[1,0,1]
	v_pk_fma_f32 v[122:123], v[120:121], 0.5, v[156:157] op_sel_hi:[1,0,1]
	v_mul_f32_e32 v120, v125, v125
	v_mul_f32_e32 v121, v127, v127
	v_fmac_f32_e32 v120, v124, v124
	v_fmac_f32_e32 v121, v126, v126
	v_add_f32_e32 v120, v120, v121
	v_mul_f32_e32 v121, v123, v123
	v_mul_f32_e32 v155, v159, v159
	v_fmac_f32_e32 v121, v122, v122
	v_fmac_f32_e32 v155, v158, v158
	v_add_f32_e32 v121, v121, v155
	v_lshlrev_b64 v[156:157], 1, v[164:165]
	v_add_f32_e32 v155, v120, v121
	v_cvt_pk_bf16_f32 v120, v124, v125
	v_lshl_add_u64 v[124:125], s[96:97], 0, v[156:157]
	v_cvt_pk_bf16_f32 v121, v126, v127
	v_cvt_pk_bf16_f32 v122, v122, v123
	v_cvt_pk_bf16_f32 v123, v158, v159
	global_store_dwordx4 v[124:125], v[120:123], off
	global_load_dwordx4 v[120:123], v[168:169], off offset:528
	s_nop 0
	global_load_dwordx4 v[124:127], v[168:169], off offset:512
	v_or_b32_e32 v156, 0x100, v156
	s_waitcnt vmcnt(1)
	v_pk_fma_f32 v[122:123], v[114:115], 0.5, v[122:123] op_sel_hi:[1,0,1]
	s_waitcnt vmcnt(0)
	v_pk_fma_f32 v[118:119], v[118:119], 0.5, v[126:127] op_sel_hi:[1,0,1]
	v_pk_fma_f32 v[116:117], v[116:117], 0.5, v[124:125] op_sel_hi:[1,0,1]
	v_pk_fma_f32 v[114:115], v[112:113], 0.5, v[120:121] op_sel_hi:[1,0,1]
	v_mul_f32_e32 v112, v117, v117
	v_mul_f32_e32 v113, v119, v119
	v_fmac_f32_e32 v112, v116, v116
	v_fmac_f32_e32 v113, v118, v118
	v_add_f32_e32 v112, v112, v113
	v_mul_f32_e32 v113, v115, v115
	v_mul_f32_e32 v120, v123, v123
	v_fmac_f32_e32 v113, v114, v114
	v_fmac_f32_e32 v120, v122, v122
	v_add_f32_e32 v113, v113, v120
	v_add_f32_e32 v112, v112, v113
	v_add_f32_e32 v120, v155, v112
	v_cvt_pk_bf16_f32 v112, v116, v117
	v_cvt_pk_bf16_f32 v113, v118, v119
	v_lshl_add_u64 v[116:117], s[96:97], 0, v[156:157]
	v_cvt_pk_bf16_f32 v114, v114, v115
	v_cvt_pk_bf16_f32 v115, v122, v123
	global_store_dwordx4 v[116:117], v[112:115], off
	s_nop 1
	v_and_b32_e32 v113, 64, v154
	v_xor_b32_e32 v112, 16, v154
	v_add_u32_e32 v113, 64, v113
	v_cmp_lt_i32_e32 vcc, v112, v113
	v_xor_b32_e32 v115, 32, v154
	s_nop 0
	v_cndmask_b32_e32 v112, v154, v112, vcc
	v_lshlrev_b32_e32 v114, 2, v112
	ds_bpermute_b32 v112, v114, v120
	v_cmp_lt_i32_e32 vcc, v115, v113
	s_waitcnt lgkmcnt(0)
	v_add_f32_e32 v112, v120, v112
	v_cndmask_b32_e32 v113, v154, v115, vcc
	v_lshlrev_b32_e32 v115, 2, v113
	v_mov_b32_e32 v113, v112
	s_nop 1
	v_permlane32_swap_b32 v112, v113
	s_and_saveexec_b64 s[44:45], s[40:41]
	s_cbranch_execz .LBB0_261
	v_lshl_add_u64 v[116:117], v[146:147], 2, s[48:49]
	s_waitcnt lgkmcnt(0)
	v_add_f32_e32 v112, v112, v113
	global_atomic_add_f32 v[116:117], v112, off
.LBB0_261:
	s_or_b64 exec, exec, s[44:45]
	v_or_b32_e32 v112, 16, v146
	s_waitcnt lgkmcnt(0)
	v_ashrrev_i32_e32 v113, 31, v112
	v_lshlrev_b64 v[116:117], 10, v[112:113]
	v_lshl_add_u64 v[124:125], v[116:117], 0, v[144:145]
	v_lshl_add_u64 v[126:127], v[124:125], 2, s[12:13]
	global_load_dwordx4 v[116:119], v[126:127], off offset:16
	global_load_dwordx4 v[120:123], v[126:127], off
	s_waitcnt vmcnt(1)
	v_pk_fma_f32 v[118:119], v[106:107], 0.5, v[118:119] op_sel_hi:[1,0,1]
	s_waitcnt vmcnt(0)
	v_pk_fma_f32 v[110:111], v[110:111], 0.5, v[122:123] op_sel_hi:[1,0,1]
	v_pk_fma_f32 v[108:109], v[108:109], 0.5, v[120:121] op_sel_hi:[1,0,1]
	v_pk_fma_f32 v[106:107], v[104:105], 0.5, v[116:117] op_sel_hi:[1,0,1]
	v_mul_f32_e32 v104, v109, v109
	v_mul_f32_e32 v105, v111, v111
	v_fmac_f32_e32 v104, v108, v108
	v_fmac_f32_e32 v105, v110, v110
	v_add_f32_e32 v104, v104, v105
	v_mul_f32_e32 v105, v107, v107
	v_mul_f32_e32 v116, v119, v119
	v_fmac_f32_e32 v105, v106, v106
	v_fmac_f32_e32 v116, v118, v118
	v_add_f32_e32 v105, v105, v116
	v_lshlrev_b64 v[116:117], 1, v[124:125]
	v_add_f32_e32 v120, v104, v105
	v_cvt_pk_bf16_f32 v104, v108, v109
	v_lshl_add_u64 v[108:109], s[96:97], 0, v[116:117]
	v_cvt_pk_bf16_f32 v105, v110, v111
	v_cvt_pk_bf16_f32 v106, v106, v107
	v_cvt_pk_bf16_f32 v107, v118, v119
	global_store_dwordx4 v[108:109], v[104:107], off
	global_load_dwordx4 v[104:107], v[126:127], off offset:528
	s_nop 0
	global_load_dwordx4 v[108:111], v[126:127], off offset:512
	v_or_b32_e32 v116, 0x100, v116
	s_waitcnt vmcnt(1)
	v_pk_fma_f32 v[106:107], v[98:99], 0.5, v[106:107] op_sel_hi:[1,0,1]
	s_waitcnt vmcnt(0)
	v_pk_fma_f32 v[102:103], v[102:103], 0.5, v[110:111] op_sel_hi:[1,0,1]
	v_pk_fma_f32 v[100:101], v[100:101], 0.5, v[108:109] op_sel_hi:[1,0,1]
	v_pk_fma_f32 v[98:99], v[96:97], 0.5, v[104:105] op_sel_hi:[1,0,1]
	v_mul_f32_e32 v96, v101, v101
	v_mul_f32_e32 v97, v103, v103
	v_fmac_f32_e32 v96, v100, v100
	v_fmac_f32_e32 v97, v102, v102
	v_add_f32_e32 v96, v96, v97
	v_mul_f32_e32 v97, v99, v99
	v_mul_f32_e32 v104, v107, v107
	v_fmac_f32_e32 v97, v98, v98
	v_fmac_f32_e32 v104, v106, v106
	v_add_f32_e32 v97, v97, v104
	v_add_f32_e32 v96, v96, v97
	v_add_f32_e32 v104, v120, v96
	v_cvt_pk_bf16_f32 v96, v100, v101
	v_lshl_add_u64 v[100:101], s[96:97], 0, v[116:117]
	v_cvt_pk_bf16_f32 v97, v102, v103
	v_cvt_pk_bf16_f32 v98, v98, v99
	v_cvt_pk_bf16_f32 v99, v106, v107
	global_store_dwordx4 v[100:101], v[96:99], off
	ds_bpermute_b32 v96, v114, v104
	s_waitcnt lgkmcnt(0)
	v_add_f32_e32 v96, v104, v96
	v_mov_b32_e32 v97, v96
	s_nop 1
	v_permlane32_swap_b32 v96, v97
	s_and_saveexec_b64 s[44:45], s[40:41]
	s_cbranch_execz .LBB0_263
	v_lshl_add_u64 v[98:99], v[112:113], 2, s[48:49]
	s_waitcnt lgkmcnt(0)
	v_add_f32_e32 v96, v96, v97
	global_atomic_add_f32 v[98:99], v96, off
; __device__ __forceinline__ float sq4(f32x4 a) { return (a.x * a.x + a.y * a.y) + (a.z * a.z + a.w * a.w); }
; __device__ __forceinline__ u32x4 pack8(f32x4 a, f32x4 b) { u32x4 o; o.x = cvt_pk(a.x, a.y); o.y = cvt_pk(a.z, a.w); o.z = cvt_pk(b.x, b.y); o.w = cvt_pk(b.z, b.w); return o; }
; __device__ __forceinline__ void row_stat_add(float* SS, int row, float v, int fq) {
;     v += __shfl_xor(v, 16); v += __shfl_xor(v, 32);
;     if (fq == 0) unsafeAtomicAdd(SS + row, v);
;     __device__ __forceinline__ void operator()(const f32x4 (&acc)[2][2][4][2], const pg8::Unit& u, int wr, int wc, int fr, int fq) const {
;     ...
;         for (int ai = 0; ai < 2; ++ai)
; #pragma unroll
;             for (int m = 0; m < 4; ++m) {
;                 const int row = row0 + ai * 128 + m * 16; float ssq = 0.f;
; #pragma unroll
;                 for (int bj = 0; bj < 2; ++bj) {
;                     const size_t idx = (size_t)row * D + col0 + bj * 128;
;                     f32x4 r0, r1;
;                     if (RF32) { r0 = *(const f32x4*)(R + idx); r1 = *(const f32x4*)(R + idx + 4); }
;                     else { const u32x4 w = *(const u32x4*)(X + idx); r0 = (f32x4){bflo(w.x), bfhi(w.x), bflo(w.y), bfhi(w.y)}; r1 = (f32x4){bflo(w.z), bfhi(w.z), bflo(w.w), bfhi(w.w)}; }
;                     const f32x4 v0 = r0 + acc[ai][bj][m][0] * s, v1 = r1 + acc[ai][bj][m][1] * s;
;                     ssq += sq4(v0) + sq4(v1);
;                     *(u32x4*)(X + idx) = pack8(v0, v1);
;                 }
;                 row_stat_add(SS, row, ssq, fq);
.LBB0_263:
	s_or_b64 exec, exec, s[44:45]
	v_or_b32_e32 v96, 32, v146
	s_waitcnt lgkmcnt(0)
	v_ashrrev_i32_e32 v97, 31, v96
	v_lshlrev_b64 v[98:99], 10, v[96:97]
	v_lshl_add_u64 v[106:107], v[98:99], 0, v[144:145]
	v_lshl_add_u64 v[108:109], v[106:107], 2, s[12:13]
	global_load_dwordx4 v[98:101], v[108:109], off offset:16
	global_load_dwordx4 v[102:105], v[108:109], off
	s_waitcnt vmcnt(1)
	v_pk_fma_f32 v[100:101], v[90:91], 0.5, v[100:101] op_sel_hi:[1,0,1]
	s_waitcnt vmcnt(0)
	v_pk_fma_f32 v[94:95], v[94:95], 0.5, v[104:105] op_sel_hi:[1,0,1]
	v_pk_fma_f32 v[92:93], v[92:93], 0.5, v[102:103] op_sel_hi:[1,0,1]
	v_pk_fma_f32 v[90:91], v[88:89], 0.5, v[98:99] op_sel_hi:[1,0,1]
	v_mul_f32_e32 v88, v93, v93
	v_mul_f32_e32 v89, v95, v95
	v_fmac_f32_e32 v88, v92, v92
	v_fmac_f32_e32 v89, v94, v94
	v_add_f32_e32 v88, v88, v89
	v_mul_f32_e32 v89, v91, v91
	v_mul_f32_e32 v98, v101, v101
	v_fmac_f32_e32 v89, v90, v90
	v_fmac_f32_e32 v98, v100, v100
	v_add_f32_e32 v89, v89, v98
	v_lshlrev_b64 v[98:99], 1, v[106:107]
	v_add_f32_e32 v102, v88, v89
	v_cvt_pk_bf16_f32 v88, v92, v93
	v_lshl_add_u64 v[92:93], s[96:97], 0, v[98:99]
	v_cvt_pk_bf16_f32 v89, v94, v95
	v_cvt_pk_bf16_f32 v90, v90, v91
	v_cvt_pk_bf16_f32 v91, v100, v101
	global_store_dwordx4 v[92:93], v[88:91], off
	global_load_dwordx4 v[88:91], v[108:109], off offset:528
	s_nop 0
	global_load_dwordx4 v[92:95], v[108:109], off offset:512
	v_or_b32_e32 v98, 0x100, v98
	s_waitcnt vmcnt(1)
	v_pk_fma_f32 v[90:91], v[82:83], 0.5, v[90:91] op_sel_hi:[1,0,1]
	s_waitcnt vmcnt(0)
	v_pk_fma_f32 v[86:87], v[86:87], 0.5, v[94:95] op_sel_hi:[1,0,1]
	v_pk_fma_f32 v[84:85], v[84:85], 0.5, v[92:93] op_sel_hi:[1,0,1]
	v_pk_fma_f32 v[82:83], v[80:81], 0.5, v[88:89] op_sel_hi:[1,0,1]
	v_mul_f32_e32 v80, v85, v85
	v_mul_f32_e32 v81, v87, v87
	v_fmac_f32_e32 v80, v84, v84
	v_fmac_f32_e32 v81, v86, v86
	v_add_f32_e32 v80, v80, v81
	v_mul_f32_e32 v81, v83, v83
	v_mul_f32_e32 v88, v91, v91
	v_fmac_f32_e32 v81, v82, v82
	v_fmac_f32_e32 v88, v90, v90
	v_add_f32_e32 v81, v81, v88
	v_add_f32_e32 v80, v80, v81
	v_add_f32_e32 v88, v102, v80
	v_cvt_pk_bf16_f32 v80, v84, v85
	v_lshl_add_u64 v[84:85], s[96:97], 0, v[98:99]
	v_cvt_pk_bf16_f32 v81, v86, v87
	v_cvt_pk_bf16_f32 v82, v82, v83
	v_cvt_pk_bf16_f32 v83, v90, v91
	global_store_dwordx4 v[84:85], v[80:83], off
	ds_bpermute_b32 v80, v114, v88
	s_waitcnt lgkmcnt(0)
	v_add_f32_e32 v80, v88, v80
	v_mov_b32_e32 v81, v80
	s_nop 1
	v_permlane32_swap_b32 v80, v81
	s_and_saveexec_b64 s[44:45], s[40:41]
	s_cbranch_execz .LBB0_265
	v_lshl_add_u64 v[82:83], v[96:97], 2, s[48:49]
	s_waitcnt lgkmcnt(0)
	v_add_f32_e32 v80, v80, v81
	global_atomic_add_f32 v[82:83], v80, off
.LBB0_265:
	s_or_b64 exec, exec, s[44:45]
	v_or_b32_e32 v80, 48, v146
	s_waitcnt lgkmcnt(0)
	v_ashrrev_i32_e32 v81, 31, v80
	v_lshlrev_b64 v[82:83], 10, v[80:81]
	v_lshl_add_u64 v[90:91], v[82:83], 0, v[144:145]
	v_lshl_add_u64 v[92:93], v[90:91], 2, s[12:13]
	global_load_dwordx4 v[82:85], v[92:93], off offset:16
	global_load_dwordx4 v[86:89], v[92:93], off
	s_waitcnt vmcnt(1)
	v_pk_fma_f32 v[84:85], v[74:75], 0.5, v[84:85] op_sel_hi:[1,0,1]
	s_waitcnt vmcnt(0)
	v_pk_fma_f32 v[78:79], v[78:79], 0.5, v[88:89] op_sel_hi:[1,0,1]
	v_pk_fma_f32 v[76:77], v[76:77], 0.5, v[86:87] op_sel_hi:[1,0,1]
	v_pk_fma_f32 v[74:75], v[72:73], 0.5, v[82:83] op_sel_hi:[1,0,1]
	v_mul_f32_e32 v72, v77, v77
	v_mul_f32_e32 v73, v79, v79
	v_fmac_f32_e32 v72, v76, v76
	v_fmac_f32_e32 v73, v78, v78
	v_add_f32_e32 v72, v72, v73
	v_mul_f32_e32 v73, v75, v75
	v_mul_f32_e32 v82, v85, v85
	v_fmac_f32_e32 v73, v74, v74
	v_fmac_f32_e32 v82, v84, v84
	v_add_f32_e32 v73, v73, v82
	v_lshlrev_b64 v[82:83], 1, v[90:91]
	v_add_f32_e32 v86, v72, v73
	v_cvt_pk_bf16_f32 v72, v76, v77
	v_lshl_add_u64 v[76:77], s[96:97], 0, v[82:83]
	v_cvt_pk_bf16_f32 v73, v78, v79
	v_cvt_pk_bf16_f32 v74, v74, v75
	v_cvt_pk_bf16_f32 v75, v84, v85
	global_store_dwordx4 v[76:77], v[72:75], off
	global_load_dwordx4 v[72:75], v[92:93], off offset:528
	s_nop 0
	global_load_dwordx4 v[76:79], v[92:93], off offset:512
	v_or_b32_e32 v82, 0x100, v82
	s_waitcnt vmcnt(1)
	v_pk_fma_f32 v[74:75], v[66:67], 0.5, v[74:75] op_sel_hi:[1,0,1]
	s_waitcnt vmcnt(0)
	v_pk_fma_f32 v[70:71], v[70:71], 0.5, v[78:79] op_sel_hi:[1,0,1]
	v_pk_fma_f32 v[68:69], v[68:69], 0.5, v[76:77] op_sel_hi:[1,0,1]
	v_pk_fma_f32 v[66:67], v[64:65], 0.5, v[72:73] op_sel_hi:[1,0,1]
	v_mul_f32_e32 v64, v69, v69
	v_mul_f32_e32 v65, v71, v71
	v_fmac_f32_e32 v64, v68, v68
	v_fmac_f32_e32 v65, v70, v70
	v_add_f32_e32 v64, v64, v65
	v_mul_f32_e32 v65, v67, v67
	v_mul_f32_e32 v72, v75, v75
	v_fmac_f32_e32 v65, v66, v66
	v_fmac_f32_e32 v72, v74, v74
	v_add_f32_e32 v65, v65, v72
	v_add_f32_e32 v64, v64, v65
	v_add_f32_e32 v72, v86, v64
	v_cvt_pk_bf16_f32 v64, v68, v69
	v_lshl_add_u64 v[68:69], s[96:97], 0, v[82:83]
	v_cvt_pk_bf16_f32 v65, v70, v71
	v_cvt_pk_bf16_f32 v66, v66, v67
	v_cvt_pk_bf16_f32 v67, v74, v75
	global_store_dwordx4 v[68:69], v[64:67], off
	ds_bpermute_b32 v64, v114, v72
	s_waitcnt lgkmcnt(0)
	v_add_f32_e32 v64, v72, v64
	v_mov_b32_e32 v65, v64
	s_nop 1
	v_permlane32_swap_b32 v64, v65
	s_and_saveexec_b64 s[44:45], s[40:41]
	s_cbranch_execz .LBB0_267
	v_lshl_add_u64 v[66:67], v[80:81], 2, s[48:49]
	s_waitcnt lgkmcnt(0)
	v_add_f32_e32 v64, v64, v65
	global_atomic_add_f32 v[66:67], v64, off
; __device__ __forceinline__ float sq4(f32x4 a) { return (a.x * a.x + a.y * a.y) + (a.z * a.z + a.w * a.w); }
; __device__ __forceinline__ u32x4 pack8(f32x4 a, f32x4 b) { u32x4 o; o.x = cvt_pk(a.x, a.y); o.y = cvt_pk(a.z, a.w); o.z = cvt_pk(b.x, b.y); o.w = cvt_pk(b.z, b.w); return o; }
; __device__ __forceinline__ void row_stat_add(float* SS, int row, float v, int fq) {
;     v += __shfl_xor(v, 16); v += __shfl_xor(v, 32);
;     if (fq == 0) unsafeAtomicAdd(SS + row, v);
;     __device__ __forceinline__ void operator()(const f32x4 (&acc)[2][2][4][2], const pg8::Unit& u, int wr, int wc, int fr, int fq) const {
;     ...
;         for (int ai = 0; ai < 2; ++ai)
; #pragma unroll
;             for (int m = 0; m < 4; ++m) {
;                 const int row = row0 + ai * 128 + m * 16; float ssq = 0.f;
; #pragma unroll
;                 for (int bj = 0; bj < 2; ++bj) {
;                     const size_t idx = (size_t)row * D + col0 + bj * 128;
;                     f32x4 r0, r1;
;                     if (RF32) { r0 = *(const f32x4*)(R + idx); r1 = *(const f32x4*)(R + idx + 4); }
;                     else { const u32x4 w = *(const u32x4*)(X + idx); r0 = (f32x4){bflo(w.x), bfhi(w.x), bflo(w.y), bfhi(w.y)}; r1 = (f32x4){bflo(w.z), bfhi(w.z), bflo(w.w), bfhi(w.w)}; }
;                     const f32x4 v0 = r0 + acc[ai][bj][m][0] * s, v1 = r1 + acc[ai][bj][m][1] * s;
;                     ssq += sq4(v0) + sq4(v1);
;                     *(u32x4*)(X + idx) = pack8(v0, v1);
;                 }
;                 row_stat_add(SS, row, ssq, fq);
.LBB0_267:
	s_or_b64 exec, exec, s[44:45]
	v_add_u32_e32 v64, 0x80, v146
	s_waitcnt lgkmcnt(0)
	v_ashrrev_i32_e32 v65, 31, v64
	v_lshlrev_b64 v[66:67], 10, v[64:65]
	v_lshl_add_u64 v[74:75], v[66:67], 0, v[144:145]
	v_lshl_add_u64 v[76:77], v[74:75], 2, s[12:13]
	global_load_dwordx4 v[66:69], v[76:77], off offset:16
	global_load_dwordx4 v[70:73], v[76:77], off
	s_waitcnt vmcnt(1)
	v_pk_fma_f32 v[68:69], v[58:59], 0.5, v[68:69] op_sel_hi:[1,0,1]
	s_waitcnt vmcnt(0)
	v_pk_fma_f32 v[62:63], v[62:63], 0.5, v[72:73] op_sel_hi:[1,0,1]
	v_pk_fma_f32 v[60:61], v[60:61], 0.5, v[70:71] op_sel_hi:[1,0,1]
	v_pk_fma_f32 v[58:59], v[56:57], 0.5, v[66:67] op_sel_hi:[1,0,1]
	v_mul_f32_e32 v56, v61, v61
	v_mul_f32_e32 v57, v63, v63
	v_fmac_f32_e32 v56, v60, v60
	v_fmac_f32_e32 v57, v62, v62
	v_add_f32_e32 v56, v56, v57
	v_mul_f32_e32 v57, v59, v59
	v_mul_f32_e32 v66, v69, v69
	v_fmac_f32_e32 v57, v58, v58
	v_fmac_f32_e32 v66, v68, v68
	v_add_f32_e32 v57, v57, v66
	v_lshlrev_b64 v[66:67], 1, v[74:75]
	v_add_f32_e32 v70, v56, v57
	v_cvt_pk_bf16_f32 v56, v60, v61
	v_lshl_add_u64 v[60:61], s[96:97], 0, v[66:67]
	v_cvt_pk_bf16_f32 v57, v62, v63
	v_cvt_pk_bf16_f32 v58, v58, v59
	v_cvt_pk_bf16_f32 v59, v68, v69
	global_store_dwordx4 v[60:61], v[56:59], off
	global_load_dwordx4 v[56:59], v[76:77], off offset:528
	s_nop 0
	global_load_dwordx4 v[60:63], v[76:77], off offset:512
	v_or_b32_e32 v66, 0x100, v66
	s_waitcnt vmcnt(1)
	v_pk_fma_f32 v[58:59], v[50:51], 0.5, v[58:59] op_sel_hi:[1,0,1]
	s_waitcnt vmcnt(0)
	v_pk_fma_f32 v[54:55], v[54:55], 0.5, v[62:63] op_sel_hi:[1,0,1]
	v_pk_fma_f32 v[52:53], v[52:53], 0.5, v[60:61] op_sel_hi:[1,0,1]
	v_pk_fma_f32 v[50:51], v[48:49], 0.5, v[56:57] op_sel_hi:[1,0,1]
	v_mul_f32_e32 v48, v53, v53
	v_mul_f32_e32 v49, v55, v55
	v_fmac_f32_e32 v48, v52, v52
	v_fmac_f32_e32 v49, v54, v54
	v_add_f32_e32 v48, v48, v49
	v_mul_f32_e32 v49, v51, v51
	v_mul_f32_e32 v56, v59, v59
	v_fmac_f32_e32 v49, v50, v50
	v_fmac_f32_e32 v56, v58, v58
	v_add_f32_e32 v49, v49, v56
	v_add_f32_e32 v48, v48, v49
	v_add_f32_e32 v56, v70, v48
	v_cvt_pk_bf16_f32 v48, v52, v53
	v_lshl_add_u64 v[52:53], s[96:97], 0, v[66:67]
	v_cvt_pk_bf16_f32 v49, v54, v55
	v_cvt_pk_bf16_f32 v50, v50, v51
	v_cvt_pk_bf16_f32 v51, v58, v59
	global_store_dwordx4 v[52:53], v[48:51], off
	ds_bpermute_b32 v48, v114, v56
	s_waitcnt lgkmcnt(0)
	v_add_f32_e32 v48, v56, v48
	v_mov_b32_e32 v49, v48
	s_nop 1
	v_permlane32_swap_b32 v48, v49
	s_and_saveexec_b64 s[44:45], s[40:41]
	s_cbranch_execz .LBB0_269
	v_lshl_add_u64 v[50:51], v[64:65], 2, s[48:49]
	s_waitcnt lgkmcnt(0)
	v_add_f32_e32 v48, v48, v49
	global_atomic_add_f32 v[50:51], v48, off
.LBB0_269:
	s_or_b64 exec, exec, s[44:45]
	v_add_u32_e32 v48, 0x90, v146
	s_waitcnt lgkmcnt(0)
	v_ashrrev_i32_e32 v49, 31, v48
	v_lshlrev_b64 v[50:51], 10, v[48:49]
	v_lshl_add_u64 v[58:59], v[50:51], 0, v[144:145]
	v_lshl_add_u64 v[60:61], v[58:59], 2, s[12:13]
	global_load_dwordx4 v[50:53], v[60:61], off offset:16
	global_load_dwordx4 v[54:57], v[60:61], off
	s_waitcnt vmcnt(1)
	v_pk_fma_f32 v[52:53], v[42:43], 0.5, v[52:53] op_sel_hi:[1,0,1]
	s_waitcnt vmcnt(0)
	v_pk_fma_f32 v[46:47], v[46:47], 0.5, v[56:57] op_sel_hi:[1,0,1]
	v_pk_fma_f32 v[44:45], v[44:45], 0.5, v[54:55] op_sel_hi:[1,0,1]
	v_pk_fma_f32 v[42:43], v[40:41], 0.5, v[50:51] op_sel_hi:[1,0,1]
	v_mul_f32_e32 v40, v45, v45
	v_mul_f32_e32 v41, v47, v47
	v_fmac_f32_e32 v40, v44, v44
	v_fmac_f32_e32 v41, v46, v46
	v_add_f32_e32 v40, v40, v41
	v_mul_f32_e32 v41, v43, v43
	v_mul_f32_e32 v50, v53, v53
	v_fmac_f32_e32 v41, v42, v42
	v_fmac_f32_e32 v50, v52, v52
	v_add_f32_e32 v41, v41, v50
	v_lshlrev_b64 v[50:51], 1, v[58:59]
	v_add_f32_e32 v54, v40, v41
	v_cvt_pk_bf16_f32 v40, v44, v45
	v_lshl_add_u64 v[44:45], s[96:97], 0, v[50:51]
	v_cvt_pk_bf16_f32 v41, v46, v47
	v_cvt_pk_bf16_f32 v42, v42, v43
	v_cvt_pk_bf16_f32 v43, v52, v53
	global_store_dwordx4 v[44:45], v[40:43], off
	global_load_dwordx4 v[40:43], v[60:61], off offset:528
	s_nop 0
	global_load_dwordx4 v[44:47], v[60:61], off offset:512
	v_or_b32_e32 v50, 0x100, v50
	s_waitcnt vmcnt(1)
	v_pk_fma_f32 v[42:43], v[34:35], 0.5, v[42:43] op_sel_hi:[1,0,1]
	s_waitcnt vmcnt(0)
	v_pk_fma_f32 v[38:39], v[38:39], 0.5, v[46:47] op_sel_hi:[1,0,1]
	v_pk_fma_f32 v[36:37], v[36:37], 0.5, v[44:45] op_sel_hi:[1,0,1]
	v_pk_fma_f32 v[34:35], v[32:33], 0.5, v[40:41] op_sel_hi:[1,0,1]
	v_mul_f32_e32 v32, v37, v37
	v_mul_f32_e32 v33, v39, v39
	v_fmac_f32_e32 v32, v36, v36
	v_fmac_f32_e32 v33, v38, v38
	v_add_f32_e32 v32, v32, v33
	v_mul_f32_e32 v33, v35, v35
	v_mul_f32_e32 v40, v43, v43
	v_fmac_f32_e32 v33, v34, v34
	v_fmac_f32_e32 v40, v42, v42
	v_add_f32_e32 v33, v33, v40
	v_add_f32_e32 v32, v32, v33
	v_add_f32_e32 v40, v54, v32
	v_cvt_pk_bf16_f32 v32, v36, v37
	v_lshl_add_u64 v[36:37], s[96:97], 0, v[50:51]
	v_cvt_pk_bf16_f32 v33, v38, v39
	v_cvt_pk_bf16_f32 v34, v34, v35
	v_cvt_pk_bf16_f32 v35, v42, v43
	global_store_dwordx4 v[36:37], v[32:35], off
	ds_bpermute_b32 v32, v114, v40
	s_waitcnt lgkmcnt(0)
	v_add_f32_e32 v32, v40, v32
	v_mov_b32_e32 v33, v32
	s_nop 1
	v_permlane32_swap_b32 v32, v33
	s_and_saveexec_b64 s[44:45], s[40:41]
	s_cbranch_execz .LBB0_271
	v_lshl_add_u64 v[34:35], v[48:49], 2, s[48:49]
	s_waitcnt lgkmcnt(0)
	v_add_f32_e32 v32, v32, v33
	global_atomic_add_f32 v[34:35], v32, off
; __device__ __forceinline__ float sq4(f32x4 a) { return (a.x * a.x + a.y * a.y) + (a.z * a.z + a.w * a.w); }
; __device__ __forceinline__ u32x4 pack8(f32x4 a, f32x4 b) { u32x4 o; o.x = cvt_pk(a.x, a.y); o.y = cvt_pk(a.z, a.w); o.z = cvt_pk(b.x, b.y); o.w = cvt_pk(b.z, b.w); return o; }
; __device__ __forceinline__ void row_stat_add(float* SS, int row, float v, int fq) {
;     v += __shfl_xor(v, 16); v += __shfl_xor(v, 32);
;     if (fq == 0) unsafeAtomicAdd(SS + row, v);
;     __device__ __forceinline__ void operator()(const f32x4 (&acc)[2][2][4][2], const pg8::Unit& u, int wr, int wc, int fr, int fq) const {
;     ...
;         for (int ai = 0; ai < 2; ++ai)
; #pragma unroll
;             for (int m = 0; m < 4; ++m) {
;                 const int row = row0 + ai * 128 + m * 16; float ssq = 0.f;
; #pragma unroll
;                 for (int bj = 0; bj < 2; ++bj) {
;                     const size_t idx = (size_t)row * D + col0 + bj * 128;
;                     f32x4 r0, r1;
;                     if (RF32) { r0 = *(const f32x4*)(R + idx); r1 = *(const f32x4*)(R + idx + 4); }
;                     else { const u32x4 w = *(const u32x4*)(X + idx); r0 = (f32x4){bflo(w.x), bfhi(w.x), bflo(w.y), bfhi(w.y)}; r1 = (f32x4){bflo(w.z), bfhi(w.z), bflo(w.w), bfhi(w.w)}; }
;                     const f32x4 v0 = r0 + acc[ai][bj][m][0] * s, v1 = r1 + acc[ai][bj][m][1] * s;
;                     ssq += sq4(v0) + sq4(v1);
;                     *(u32x4*)(X + idx) = pack8(v0, v1);
;                 }
;                 row_stat_add(SS, row, ssq, fq);
.LBB0_271:
	s_or_b64 exec, exec, s[44:45]
	v_add_u32_e32 v32, 0xa0, v146
	s_waitcnt lgkmcnt(0)
	v_ashrrev_i32_e32 v33, 31, v32
	v_lshlrev_b64 v[34:35], 10, v[32:33]
	v_lshl_add_u64 v[42:43], v[34:35], 0, v[144:145]
	v_lshl_add_u64 v[44:45], v[42:43], 2, s[12:13]
	global_load_dwordx4 v[34:37], v[44:45], off offset:16
	global_load_dwordx4 v[38:41], v[44:45], off
	s_waitcnt vmcnt(1)
	v_pk_fma_f32 v[36:37], v[26:27], 0.5, v[36:37] op_sel_hi:[1,0,1]
	s_waitcnt vmcnt(0)
	v_pk_fma_f32 v[30:31], v[30:31], 0.5, v[40:41] op_sel_hi:[1,0,1]
	v_pk_fma_f32 v[28:29], v[28:29], 0.5, v[38:39] op_sel_hi:[1,0,1]
	v_pk_fma_f32 v[26:27], v[24:25], 0.5, v[34:35] op_sel_hi:[1,0,1]
	v_mul_f32_e32 v24, v29, v29
	v_mul_f32_e32 v25, v31, v31
	v_fmac_f32_e32 v24, v28, v28
	v_fmac_f32_e32 v25, v30, v30
	v_add_f32_e32 v24, v24, v25
	v_mul_f32_e32 v25, v27, v27
	v_mul_f32_e32 v34, v37, v37
	v_fmac_f32_e32 v25, v26, v26
	v_fmac_f32_e32 v34, v36, v36
	v_add_f32_e32 v25, v25, v34
	v_lshlrev_b64 v[34:35], 1, v[42:43]
	v_add_f32_e32 v38, v24, v25
	v_cvt_pk_bf16_f32 v24, v28, v29
	v_lshl_add_u64 v[28:29], s[96:97], 0, v[34:35]
	v_cvt_pk_bf16_f32 v25, v30, v31
	v_cvt_pk_bf16_f32 v26, v26, v27
	v_cvt_pk_bf16_f32 v27, v36, v37
	global_store_dwordx4 v[28:29], v[24:27], off
	global_load_dwordx4 v[24:27], v[44:45], off offset:528
	s_nop 0
	global_load_dwordx4 v[28:31], v[44:45], off offset:512
	v_or_b32_e32 v34, 0x100, v34
	s_waitcnt vmcnt(1)
	v_pk_fma_f32 v[26:27], v[18:19], 0.5, v[26:27] op_sel_hi:[1,0,1]
	s_waitcnt vmcnt(0)
	v_pk_fma_f32 v[22:23], v[22:23], 0.5, v[30:31] op_sel_hi:[1,0,1]
	v_pk_fma_f32 v[20:21], v[20:21], 0.5, v[28:29] op_sel_hi:[1,0,1]
	v_pk_fma_f32 v[18:19], v[16:17], 0.5, v[24:25] op_sel_hi:[1,0,1]
	v_mul_f32_e32 v16, v21, v21
	v_mul_f32_e32 v17, v23, v23
	v_fmac_f32_e32 v16, v20, v20
	v_fmac_f32_e32 v17, v22, v22
	v_add_f32_e32 v16, v16, v17
	v_mul_f32_e32 v17, v19, v19
	v_mul_f32_e32 v24, v27, v27
	v_fmac_f32_e32 v17, v18, v18
	v_fmac_f32_e32 v24, v26, v26
	v_add_f32_e32 v17, v17, v24
	v_add_f32_e32 v16, v16, v17
	v_add_f32_e32 v24, v38, v16
	v_cvt_pk_bf16_f32 v16, v20, v21
	v_lshl_add_u64 v[20:21], s[96:97], 0, v[34:35]
	v_cvt_pk_bf16_f32 v17, v22, v23
	v_cvt_pk_bf16_f32 v18, v18, v19
	v_cvt_pk_bf16_f32 v19, v26, v27
	global_store_dwordx4 v[20:21], v[16:19], off
	ds_bpermute_b32 v16, v114, v24
	s_waitcnt lgkmcnt(0)
	v_add_f32_e32 v16, v24, v16
	v_mov_b32_e32 v17, v16
	s_nop 1
	v_permlane32_swap_b32 v16, v17
	s_and_saveexec_b64 s[44:45], s[40:41]
	s_cbranch_execz .LBB0_273
	v_lshl_add_u64 v[18:19], v[32:33], 2, s[48:49]
	s_waitcnt lgkmcnt(0)
	v_add_f32_e32 v16, v16, v17
	global_atomic_add_f32 v[18:19], v16, off
.LBB0_273:
	s_or_b64 exec, exec, s[44:45]
	v_add_u32_e32 v16, 0xb0, v146
	s_waitcnt lgkmcnt(0)
	v_ashrrev_i32_e32 v17, 31, v16
	v_lshlrev_b64 v[18:19], 10, v[16:17]
	v_lshl_add_u64 v[26:27], v[18:19], 0, v[144:145]
	v_lshl_add_u64 v[28:29], v[26:27], 2, s[12:13]
	global_load_dwordx4 v[18:21], v[28:29], off offset:16
	global_load_dwordx4 v[22:25], v[28:29], off
	s_waitcnt vmcnt(1)
	v_pk_fma_f32 v[20:21], v[10:11], 0.5, v[20:21] op_sel_hi:[1,0,1]
	s_waitcnt vmcnt(0)
	v_pk_fma_f32 v[14:15], v[14:15], 0.5, v[24:25] op_sel_hi:[1,0,1]
	v_pk_fma_f32 v[12:13], v[12:13], 0.5, v[22:23] op_sel_hi:[1,0,1]
	v_pk_fma_f32 v[10:11], v[8:9], 0.5, v[18:19] op_sel_hi:[1,0,1]
	v_mul_f32_e32 v8, v13, v13
	v_mul_f32_e32 v9, v15, v15
	v_fmac_f32_e32 v8, v12, v12
	v_fmac_f32_e32 v9, v14, v14
	v_add_f32_e32 v8, v8, v9
	v_mul_f32_e32 v9, v11, v11
	v_mul_f32_e32 v18, v21, v21
	v_fmac_f32_e32 v9, v10, v10
	v_fmac_f32_e32 v18, v20, v20
	v_add_f32_e32 v9, v9, v18
	v_lshlrev_b64 v[18:19], 1, v[26:27]
	v_add_f32_e32 v22, v8, v9
	v_cvt_pk_bf16_f32 v8, v12, v13
	v_lshl_add_u64 v[12:13], s[96:97], 0, v[18:19]
	v_cvt_pk_bf16_f32 v9, v14, v15
	v_cvt_pk_bf16_f32 v10, v10, v11
	v_cvt_pk_bf16_f32 v11, v20, v21
	global_store_dwordx4 v[12:13], v[8:11], off
	global_load_dwordx4 v[8:11], v[28:29], off offset:528
	s_nop 0
	global_load_dwordx4 v[12:15], v[28:29], off offset:512
	v_or_b32_e32 v18, 0x100, v18
	s_waitcnt vmcnt(1)
	v_pk_fma_f32 v[10:11], v[2:3], 0.5, v[10:11] op_sel_hi:[1,0,1]
	s_waitcnt vmcnt(0)
	v_pk_fma_f32 v[6:7], v[6:7], 0.5, v[14:15] op_sel_hi:[1,0,1]
	v_pk_fma_f32 v[4:5], v[4:5], 0.5, v[12:13] op_sel_hi:[1,0,1]
	v_pk_fma_f32 v[2:3], v[0:1], 0.5, v[8:9] op_sel_hi:[1,0,1]
	v_mul_f32_e32 v0, v5, v5
	v_mul_f32_e32 v1, v7, v7
	v_fmac_f32_e32 v0, v4, v4
	v_fmac_f32_e32 v1, v6, v6
	v_add_f32_e32 v0, v0, v1
	v_mul_f32_e32 v1, v3, v3
	v_mul_f32_e32 v8, v11, v11
	v_fmac_f32_e32 v1, v2, v2
	v_fmac_f32_e32 v8, v10, v10
	v_add_f32_e32 v1, v1, v8
	v_add_f32_e32 v0, v0, v1
	v_add_f32_e32 v8, v22, v0
	v_cvt_pk_bf16_f32 v0, v4, v5
	v_lshl_add_u64 v[4:5], s[96:97], 0, v[18:19]
	v_cvt_pk_bf16_f32 v1, v6, v7
	v_cvt_pk_bf16_f32 v2, v2, v3
	v_cvt_pk_bf16_f32 v3, v10, v11
	global_store_dwordx4 v[4:5], v[0:3], off
	ds_bpermute_b32 v0, v114, v8
	s_waitcnt lgkmcnt(0)
	v_add_f32_e32 v0, v8, v0
	v_mov_b32_e32 v1, v0
	s_nop 1
	v_permlane32_swap_b32 v0, v1
	s_and_saveexec_b64 s[44:45], s[40:41]
	s_cbranch_execz .LBB0_275
	v_lshl_add_u64 v[2:3], v[16:17], 2, s[48:49]
	s_waitcnt lgkmcnt(0)
	v_add_f32_e32 v0, v0, v1
	global_atomic_add_f32 v[2:3], v0, off

; __device__ __forceinline__ float sq4(f32x4 a) { return (a.x * a.x + a.y * a.y) + (a.z * a.z + a.w * a.w); }
; __device__ __forceinline__ u32x4 pack8(f32x4 a, f32x4 b) { u32x4 o; o.x = cvt_pk(a.x, a.y); o.y = cvt_pk(a.z, a.w); o.z = cvt_pk(b.x, b.y); o.w = cvt_pk(b.z, b.w); return o; }
; __device__ __forceinline__ void row_stat_add(float* SS, int row, float v, int fq) {
;     v += __shfl_xor(v, 16); v += __shfl_xor(v, 32);
;     if (fq == 0) unsafeAtomicAdd(SS + row, v);
;     __device__ __forceinline__ void operator()(const f32x4 (&acc)[2][2][4][2], const pg8::Unit& u, int wr, int wc, int fr, int fq) const {
;     ...
;         for (int ai = 0; ai < 2; ++ai)
; #pragma unroll
;             for (int m = 0; m < 4; ++m) {
;                 const int row = row0 + ai * 128 + m * 16; float ssq = 0.f;
; #pragma unroll
;                 for (int bj = 0; bj < 2; ++bj) {
;                     const size_t idx = (size_t)row * D + col0 + bj * 128;
;                     f32x4 r0, r1;
;                     if (RF32) { r0 = *(const f32x4*)(R + idx); r1 = *(const f32x4*)(R + idx + 4); }
;                     else { const u32x4 w = *(const u32x4*)(X + idx); r0 = (f32x4){bflo(w.x), bfhi(w.x), bflo(w.y), bfhi(w.y)}; r1 = (f32x4){bflo(w.z), bfhi(w.z), bflo(w.w), bfhi(w.w)}; }
;                     const f32x4 v0 = r0 + acc[ai][bj][m][0] * s, v1 = r1 + acc[ai][bj][m][1] * s;
;                     ssq += sq4(v0) + sq4(v1);
;                     *(u32x4*)(X + idx) = pack8(v0, v1);
;                 }
;                 row_stat_add(SS, row, ssq, fq);
.LBB0_908:
	v_lshl_add_u32 v146, s59, 8, v148
	v_ashrrev_i32_e32 v147, 31, v146
	v_lshl_or_b32 v144, s58, 8, v150
	v_lshlrev_b64 v[156:157], 11, v[146:147]
	v_ashrrev_i32_e32 v145, 31, v144
	v_lshl_add_u64 v[156:157], s[96:97], 0, v[156:157]
	v_lshl_add_u64 v[160:161], v[144:145], 1, v[156:157]
	global_load_dwordx4 v[156:159], v[160:161], off
	global_load_dwordx4 v[168:171], v[160:161], off offset:256
	s_mov_b64 vcc, 0x8000
	v_lshl_add_u64 v[162:163], v[160:161], 0, vcc
	global_load_dwordx4 v[172:175], v[162:163], off
	global_load_dwordx4 v[176:179], v[162:163], off offset:256
	s_mov_b64 vcc, 0x10000
	v_lshl_add_u64 v[162:163], v[160:161], 0, vcc
	global_load_dwordx4 v[180:183], v[162:163], off
	global_load_dwordx4 v[184:187], v[162:163], off offset:256
	s_mov_b64 vcc, 0x18000
	v_lshl_add_u64 v[162:163], v[160:161], 0, vcc
	global_load_dwordx4 v[188:191], v[162:163], off
	global_load_dwordx4 v[192:195], v[162:163], off offset:256
	s_mov_b64 vcc, 0x40000
	v_lshl_add_u64 v[162:163], v[160:161], 0, vcc
	global_load_dwordx4 v[196:199], v[162:163], off
	global_load_dwordx4 v[200:203], v[162:163], off offset:256
	s_mov_b64 vcc, 0x48000
	v_lshl_add_u64 v[162:163], v[160:161], 0, vcc
	global_load_dwordx4 v[204:207], v[162:163], off
	global_load_dwordx4 v[208:211], v[162:163], off offset:256
	s_mov_b64 vcc, 0x50000
	v_lshl_add_u64 v[162:163], v[160:161], 0, vcc
	global_load_dwordx4 v[212:215], v[162:163], off
	global_load_dwordx4 v[216:219], v[162:163], off offset:256
	s_mov_b64 vcc, 0x58000
	v_lshl_add_u64 v[162:163], v[160:161], 0, vcc
	global_load_dwordx4 v[220:223], v[162:163], off
	s_waitcnt vmcnt(0)
	v_lshlrev_b32_e32 v162, 16, v156
	v_and_b32_e32 v163, 0xffff0000, v156
	v_lshlrev_b32_e32 v156, 16, v157
	v_and_b32_e32 v157, 0xffff0000, v157
	v_lshlrev_b32_e32 v164, 16, v158
	v_and_b32_e32 v165, 0xffff0000, v158
	v_lshlrev_b32_e32 v158, 16, v159
	v_and_b32_e32 v159, 0xffff0000, v159
	v_pk_fma_f32 v[126:127], v[126:127], 0.5, v[156:157] op_sel_hi:[1,0,1]
	v_pk_fma_f32 v[124:125], v[124:125], 0.5, v[162:163] op_sel_hi:[1,0,1]
	v_pk_fma_f32 v[156:157], v[122:123], 0.5, v[158:159] op_sel_hi:[1,0,1]
	v_pk_fma_f32 v[122:123], v[120:121], 0.5, v[164:165] op_sel_hi:[1,0,1]
	v_mul_f32_e32 v120, v125, v125
	v_mul_f32_e32 v121, v127, v127
	v_fmac_f32_e32 v120, v124, v124
	v_fmac_f32_e32 v121, v126, v126
	v_add_f32_e32 v120, v120, v121
	v_mul_f32_e32 v121, v123, v123
	v_mul_f32_e32 v155, v157, v157
	v_fmac_f32_e32 v121, v122, v122
	v_fmac_f32_e32 v155, v156, v156
	v_add_f32_e32 v121, v121, v155
	v_add_f32_e32 v155, v120, v121
	v_cvt_pk_bf16_f32 v120, v124, v125
	v_cvt_pk_bf16_f32 v121, v126, v127
	v_cvt_pk_bf16_f32 v122, v122, v123
	v_cvt_pk_bf16_f32 v123, v156, v157
	global_store_dwordx4 v[160:161], v[120:123], off
	s_nop 1
	v_mov_b64_e32 v[120:121], v[168:169]
	v_mov_b64_e32 v[122:123], v[170:171]
	v_lshlrev_b32_e32 v124, 16, v120
	v_and_b32_e32 v125, 0xffff0000, v120
	v_lshlrev_b32_e32 v120, 16, v121
	v_and_b32_e32 v121, 0xffff0000, v121
	v_lshlrev_b32_e32 v126, 16, v122
	v_and_b32_e32 v127, 0xffff0000, v122
	v_lshlrev_b32_e32 v122, 16, v123
	v_and_b32_e32 v123, 0xffff0000, v123
	v_pk_fma_f32 v[118:119], v[118:119], 0.5, v[120:121] op_sel_hi:[1,0,1]
	v_pk_fma_f32 v[116:117], v[116:117], 0.5, v[124:125] op_sel_hi:[1,0,1]
	v_pk_fma_f32 v[120:121], v[114:115], 0.5, v[122:123] op_sel_hi:[1,0,1]
	v_pk_fma_f32 v[114:115], v[112:113], 0.5, v[126:127] op_sel_hi:[1,0,1]
	v_mul_f32_e32 v112, v117, v117
	v_mul_f32_e32 v113, v119, v119
	v_fmac_f32_e32 v112, v116, v116
	v_fmac_f32_e32 v113, v118, v118
	v_add_f32_e32 v112, v112, v113
	v_mul_f32_e32 v113, v115, v115
	v_mul_f32_e32 v122, v121, v121
	v_fmac_f32_e32 v113, v114, v114
	v_fmac_f32_e32 v122, v120, v120
	v_add_f32_e32 v113, v113, v122
	v_add_f32_e32 v112, v112, v113
	v_add_f32_e32 v122, v155, v112
	v_cvt_pk_bf16_f32 v112, v116, v117
	v_cvt_pk_bf16_f32 v113, v118, v119
	v_cvt_pk_bf16_f32 v114, v114, v115
	v_cvt_pk_bf16_f32 v115, v120, v121
	global_store_dwordx4 v[160:161], v[112:115], off offset:256
	s_nop 1
	v_and_b32_e32 v113, 64, v154
	v_xor_b32_e32 v112, 16, v154
	v_add_u32_e32 v113, 64, v113
	v_cmp_lt_i32_e32 vcc, v112, v113
	v_xor_b32_e32 v115, 32, v154
	s_nop 0
	v_cndmask_b32_e32 v112, v154, v112, vcc
	v_lshlrev_b32_e32 v114, 2, v112
	ds_bpermute_b32 v112, v114, v122
	v_cmp_lt_i32_e32 vcc, v115, v113
	s_waitcnt lgkmcnt(0)
	v_add_f32_e32 v112, v122, v112
	v_cndmask_b32_e32 v113, v154, v115, vcc
	v_lshlrev_b32_e32 v115, 2, v113
	v_mov_b32_e32 v113, v112
	s_nop 1
	v_permlane32_swap_b32 v112, v113
	s_and_saveexec_b64 s[44:45], s[36:37]
	s_cbranch_execz .LBB0_910
	v_lshl_add_u64 v[116:117], v[146:147], 2, s[12:13]
	s_waitcnt lgkmcnt(0)
	v_add_f32_e32 v112, v112, v113
	global_atomic_add_f32 v[116:117], v112, off
; __device__ __forceinline__ float sq4(f32x4 a) { return (a.x * a.x + a.y * a.y) + (a.z * a.z + a.w * a.w); }
; __device__ __forceinline__ u32x4 pack8(f32x4 a, f32x4 b) { u32x4 o; o.x = cvt_pk(a.x, a.y); o.y = cvt_pk(a.z, a.w); o.z = cvt_pk(b.x, b.y); o.w = cvt_pk(b.z, b.w); return o; }
; __device__ __forceinline__ void row_stat_add(float* SS, int row, float v, int fq) {
;     v += __shfl_xor(v, 16); v += __shfl_xor(v, 32);
;     if (fq == 0) unsafeAtomicAdd(SS + row, v);
;     __device__ __forceinline__ void operator()(const f32x4 (&acc)[2][2][4][2], const pg8::Unit& u, int wr, int wc, int fr, int fq) const {
;     ...
;         for (int ai = 0; ai < 2; ++ai)
; #pragma unroll
;             for (int m = 0; m < 4; ++m) {
;                 const int row = row0 + ai * 128 + m * 16; float ssq = 0.f;
; #pragma unroll
;                 for (int bj = 0; bj < 2; ++bj) {
;                     const size_t idx = (size_t)row * D + col0 + bj * 128;
;                     f32x4 r0, r1;
;                     if (RF32) { r0 = *(const f32x4*)(R + idx); r1 = *(const f32x4*)(R + idx + 4); }
;                     else { const u32x4 w = *(const u32x4*)(X + idx); r0 = (f32x4){bflo(w.x), bfhi(w.x), bflo(w.y), bfhi(w.y)}; r1 = (f32x4){bflo(w.z), bfhi(w.z), bflo(w.w), bfhi(w.w)}; }
;                     const f32x4 v0 = r0 + acc[ai][bj][m][0] * s, v1 = r1 + acc[ai][bj][m][1] * s;
;                     ssq += sq4(v0) + sq4(v1);
;                     *(u32x4*)(X + idx) = pack8(v0, v1);
;                 }
;                 row_stat_add(SS, row, ssq, fq);
.LBB0_910:
	s_or_b64 exec, exec, s[44:45]
	v_or_b32_e32 v112, 16, v146
	s_waitcnt lgkmcnt(0)
	v_ashrrev_i32_e32 v113, 31, v112
	v_lshlrev_b64 v[116:117], 11, v[112:113]
	v_lshl_add_u64 v[116:117], s[96:97], 0, v[116:117]
	v_lshl_add_u64 v[120:121], v[144:145], 1, v[116:117]
	s_nop 1
	v_mov_b64_e32 v[116:117], v[172:173]
	v_mov_b64_e32 v[118:119], v[174:175]
	v_lshlrev_b32_e32 v122, 16, v116
	v_and_b32_e32 v123, 0xffff0000, v116
	v_lshlrev_b32_e32 v116, 16, v117
	v_and_b32_e32 v117, 0xffff0000, v117
	v_lshlrev_b32_e32 v124, 16, v118
	v_and_b32_e32 v125, 0xffff0000, v118
	v_lshlrev_b32_e32 v118, 16, v119
	v_and_b32_e32 v119, 0xffff0000, v119
	v_pk_fma_f32 v[116:117], v[110:111], 0.5, v[116:117] op_sel_hi:[1,0,1]
	v_pk_fma_f32 v[122:123], v[108:109], 0.5, v[122:123] op_sel_hi:[1,0,1]
	v_pk_fma_f32 v[118:119], v[106:107], 0.5, v[118:119] op_sel_hi:[1,0,1]
	v_pk_fma_f32 v[124:125], v[104:105], 0.5, v[124:125] op_sel_hi:[1,0,1]
	v_cvt_pk_bf16_f32 v104, v122, v123
	v_cvt_pk_bf16_f32 v105, v116, v117
	v_mul_f32_e32 v123, v123, v123
	v_cvt_pk_bf16_f32 v106, v124, v125
	v_cvt_pk_bf16_f32 v107, v118, v119
	s_nop 1
	v_mov_b64_e32 v[108:109], v[176:177]
	v_mov_b64_e32 v[110:111], v[178:179]
	v_mul_f32_e32 v117, v117, v117
	v_mul_f32_e32 v125, v125, v125
	v_mul_f32_e32 v119, v119, v119
	v_fmac_f32_e32 v123, v122, v122
	v_fmac_f32_e32 v117, v116, v116
	v_fmac_f32_e32 v125, v124, v124
	v_fmac_f32_e32 v119, v118, v118
	v_add_f32_e32 v116, v123, v117
	v_add_f32_e32 v117, v125, v119
	v_add_f32_e32 v122, v116, v117
	global_store_dwordx4 v[120:121], v[104:107], off
	v_lshlrev_b32_e32 v116, 16, v108
	v_and_b32_e32 v117, 0xffff0000, v108
	v_lshlrev_b32_e32 v108, 16, v109
	v_and_b32_e32 v109, 0xffff0000, v109
	v_lshlrev_b32_e32 v118, 16, v110
	v_and_b32_e32 v119, 0xffff0000, v110
	v_lshlrev_b32_e32 v110, 16, v111
	v_and_b32_e32 v111, 0xffff0000, v111
	v_pk_fma_f32 v[102:103], v[102:103], 0.5, v[108:109] op_sel_hi:[1,0,1]
	v_pk_fma_f32 v[100:101], v[100:101], 0.5, v[116:117] op_sel_hi:[1,0,1]
	v_pk_fma_f32 v[108:109], v[98:99], 0.5, v[110:111] op_sel_hi:[1,0,1]
	v_pk_fma_f32 v[110:111], v[96:97], 0.5, v[118:119] op_sel_hi:[1,0,1]
	v_mul_f32_e32 v96, v101, v101
	v_mul_f32_e32 v97, v103, v103
	v_mul_f32_e32 v98, v111, v111
	v_mul_f32_e32 v99, v109, v109
	v_fmac_f32_e32 v96, v100, v100
	v_fmac_f32_e32 v97, v102, v102
	v_fmac_f32_e32 v98, v110, v110
	v_fmac_f32_e32 v99, v108, v108
	v_add_f32_e32 v96, v96, v97
	v_add_f32_e32 v97, v98, v99
	v_add_f32_e32 v96, v96, v97
	v_add_f32_e32 v96, v122, v96
	ds_bpermute_b32 v97, v114, v96
	v_cvt_pk_bf16_f32 v98, v100, v101
	v_cvt_pk_bf16_f32 v99, v102, v103
	v_cvt_pk_bf16_f32 v100, v110, v111
	v_cvt_pk_bf16_f32 v101, v108, v109
	s_waitcnt lgkmcnt(0)
	v_add_f32_e32 v96, v96, v97
	v_mov_b32_e32 v97, v96
	s_nop 1
	v_permlane32_swap_b32 v96, v97
	global_store_dwordx4 v[120:121], v[98:101], off offset:256
	s_and_saveexec_b64 s[44:45], s[36:37]
	s_cbranch_execz .LBB0_912
	v_lshl_add_u64 v[98:99], v[112:113], 2, s[12:13]
	s_waitcnt lgkmcnt(0)
	v_add_f32_e32 v96, v96, v97
	global_atomic_add_f32 v[98:99], v96, off
.LBB0_912:
	s_or_b64 exec, exec, s[44:45]
	v_or_b32_e32 v96, 32, v146
	s_waitcnt lgkmcnt(0)
	v_ashrrev_i32_e32 v97, 31, v96
	v_lshlrev_b64 v[98:99], 11, v[96:97]
	v_lshl_add_u64 v[98:99], s[96:97], 0, v[98:99]
	v_lshl_add_u64 v[102:103], v[144:145], 1, v[98:99]
	s_nop 1
	v_mov_b64_e32 v[98:99], v[180:181]
	v_mov_b64_e32 v[100:101], v[182:183]
	v_lshlrev_b32_e32 v104, 16, v98
	v_and_b32_e32 v105, 0xffff0000, v98
	v_lshlrev_b32_e32 v98, 16, v99
	v_and_b32_e32 v99, 0xffff0000, v99
	v_lshlrev_b32_e32 v106, 16, v100
	v_and_b32_e32 v107, 0xffff0000, v100
	v_lshlrev_b32_e32 v100, 16, v101
	v_and_b32_e32 v101, 0xffff0000, v101
	v_pk_fma_f32 v[98:99], v[94:95], 0.5, v[98:99] op_sel_hi:[1,0,1]
	v_pk_fma_f32 v[104:105], v[92:93], 0.5, v[104:105] op_sel_hi:[1,0,1]
	v_pk_fma_f32 v[100:101], v[90:91], 0.5, v[100:101] op_sel_hi:[1,0,1]
	v_pk_fma_f32 v[106:107], v[88:89], 0.5, v[106:107] op_sel_hi:[1,0,1]
	v_cvt_pk_bf16_f32 v88, v104, v105
	v_cvt_pk_bf16_f32 v89, v98, v99
	v_mul_f32_e32 v105, v105, v105
	v_cvt_pk_bf16_f32 v90, v106, v107
	v_cvt_pk_bf16_f32 v91, v100, v101
	s_nop 1
	v_mov_b64_e32 v[92:93], v[184:185]
	v_mov_b64_e32 v[94:95], v[186:187]
	v_mul_f32_e32 v99, v99, v99
	v_mul_f32_e32 v107, v107, v107
	v_mul_f32_e32 v101, v101, v101
	v_fmac_f32_e32 v105, v104, v104
	v_fmac_f32_e32 v99, v98, v98
	v_fmac_f32_e32 v107, v106, v106
	v_fmac_f32_e32 v101, v100, v100
	v_add_f32_e32 v98, v105, v99
	v_add_f32_e32 v99, v107, v101
	v_add_f32_e32 v104, v98, v99
	global_store_dwordx4 v[102:103], v[88:91], off
	v_lshlrev_b32_e32 v98, 16, v92
	v_and_b32_e32 v99, 0xffff0000, v92
	v_lshlrev_b32_e32 v92, 16, v93
	v_and_b32_e32 v93, 0xffff0000, v93
	v_lshlrev_b32_e32 v100, 16, v94
	v_and_b32_e32 v101, 0xffff0000, v94
	v_lshlrev_b32_e32 v94, 16, v95
	v_and_b32_e32 v95, 0xffff0000, v95
	v_pk_fma_f32 v[86:87], v[86:87], 0.5, v[92:93] op_sel_hi:[1,0,1]
	v_pk_fma_f32 v[84:85], v[84:85], 0.5, v[98:99] op_sel_hi:[1,0,1]
	v_pk_fma_f32 v[92:93], v[82:83], 0.5, v[94:95] op_sel_hi:[1,0,1]
	v_pk_fma_f32 v[94:95], v[80:81], 0.5, v[100:101] op_sel_hi:[1,0,1]
	v_mul_f32_e32 v80, v85, v85
	v_mul_f32_e32 v81, v87, v87
	v_mul_f32_e32 v82, v95, v95
	v_mul_f32_e32 v83, v93, v93
	v_fmac_f32_e32 v80, v84, v84
	v_fmac_f32_e32 v81, v86, v86
	v_fmac_f32_e32 v82, v94, v94
	v_fmac_f32_e32 v83, v92, v92
	v_add_f32_e32 v80, v80, v81
	v_add_f32_e32 v81, v82, v83
	v_add_f32_e32 v80, v80, v81
	v_add_f32_e32 v80, v104, v80
	ds_bpermute_b32 v81, v114, v80
	v_cvt_pk_bf16_f32 v82, v84, v85
	v_cvt_pk_bf16_f32 v83, v86, v87
	v_cvt_pk_bf16_f32 v84, v94, v95
	v_cvt_pk_bf16_f32 v85, v92, v93
	s_waitcnt lgkmcnt(0)
	v_add_f32_e32 v80, v80, v81
	v_mov_b32_e32 v81, v80
	s_nop 1
	v_permlane32_swap_b32 v80, v81
	global_store_dwordx4 v[102:103], v[82:85], off offset:256
	s_and_saveexec_b64 s[44:45], s[36:37]
	s_cbranch_execz .LBB0_914
	v_lshl_add_u64 v[82:83], v[96:97], 2, s[12:13]
	s_waitcnt lgkmcnt(0)
	v_add_f32_e32 v80, v80, v81
	global_atomic_add_f32 v[82:83], v80, off
; __device__ __forceinline__ float sq4(f32x4 a) { return (a.x * a.x + a.y * a.y) + (a.z * a.z + a.w * a.w); }
; __device__ __forceinline__ u32x4 pack8(f32x4 a, f32x4 b) { u32x4 o; o.x = cvt_pk(a.x, a.y); o.y = cvt_pk(a.z, a.w); o.z = cvt_pk(b.x, b.y); o.w = cvt_pk(b.z, b.w); return o; }
; __device__ __forceinline__ void row_stat_add(float* SS, int row, float v, int fq) {
;     v += __shfl_xor(v, 16); v += __shfl_xor(v, 32);
;     if (fq == 0) unsafeAtomicAdd(SS + row, v);
;     __device__ __forceinline__ void operator()(const f32x4 (&acc)[2][2][4][2], const pg8::Unit& u, int wr, int wc, int fr, int fq) const {
;     ...
;         for (int ai = 0; ai < 2; ++ai)
; #pragma unroll
;             for (int m = 0; m < 4; ++m) {
;                 const int row = row0 + ai * 128 + m * 16; float ssq = 0.f;
; #pragma unroll
;                 for (int bj = 0; bj < 2; ++bj) {
;                     const size_t idx = (size_t)row * D + col0 + bj * 128;
;                     f32x4 r0, r1;
;                     if (RF32) { r0 = *(const f32x4*)(R + idx); r1 = *(const f32x4*)(R + idx + 4); }
;                     else { const u32x4 w = *(const u32x4*)(X + idx); r0 = (f32x4){bflo(w.x), bfhi(w.x), bflo(w.y), bfhi(w.y)}; r1 = (f32x4){bflo(w.z), bfhi(w.z), bflo(w.w), bfhi(w.w)}; }
;                     const f32x4 v0 = r0 + acc[ai][bj][m][0] * s, v1 = r1 + acc[ai][bj][m][1] * s;
;                     ssq += sq4(v0) + sq4(v1);
;                     *(u32x4*)(X + idx) = pack8(v0, v1);
;                 }
;                 row_stat_add(SS, row, ssq, fq);
.LBB0_914:
	s_or_b64 exec, exec, s[44:45]
	v_or_b32_e32 v80, 48, v146
	s_waitcnt lgkmcnt(0)
	v_ashrrev_i32_e32 v81, 31, v80
	v_lshlrev_b64 v[82:83], 11, v[80:81]
	v_lshl_add_u64 v[82:83], s[96:97], 0, v[82:83]
	v_lshl_add_u64 v[86:87], v[144:145], 1, v[82:83]
	s_nop 1
	v_mov_b64_e32 v[82:83], v[188:189]
	v_mov_b64_e32 v[84:85], v[190:191]
	v_lshlrev_b32_e32 v88, 16, v82
	v_and_b32_e32 v89, 0xffff0000, v82
	v_lshlrev_b32_e32 v82, 16, v83
	v_and_b32_e32 v83, 0xffff0000, v83
	v_lshlrev_b32_e32 v90, 16, v84
	v_and_b32_e32 v91, 0xffff0000, v84
	v_lshlrev_b32_e32 v84, 16, v85
	v_and_b32_e32 v85, 0xffff0000, v85
	v_pk_fma_f32 v[82:83], v[78:79], 0.5, v[82:83] op_sel_hi:[1,0,1]
	v_pk_fma_f32 v[88:89], v[76:77], 0.5, v[88:89] op_sel_hi:[1,0,1]
	v_pk_fma_f32 v[84:85], v[74:75], 0.5, v[84:85] op_sel_hi:[1,0,1]
	v_pk_fma_f32 v[90:91], v[72:73], 0.5, v[90:91] op_sel_hi:[1,0,1]
	v_cvt_pk_bf16_f32 v72, v88, v89
	v_cvt_pk_bf16_f32 v73, v82, v83
	v_mul_f32_e32 v89, v89, v89
	v_cvt_pk_bf16_f32 v74, v90, v91
	v_cvt_pk_bf16_f32 v75, v84, v85
	s_nop 1
	v_mov_b64_e32 v[76:77], v[192:193]
	v_mov_b64_e32 v[78:79], v[194:195]
	v_mul_f32_e32 v83, v83, v83
	v_mul_f32_e32 v91, v91, v91
	v_mul_f32_e32 v85, v85, v85
	v_fmac_f32_e32 v89, v88, v88
	v_fmac_f32_e32 v83, v82, v82
	v_fmac_f32_e32 v91, v90, v90
	v_fmac_f32_e32 v85, v84, v84
	v_add_f32_e32 v82, v89, v83
	v_add_f32_e32 v83, v91, v85
	v_add_f32_e32 v88, v82, v83
	global_store_dwordx4 v[86:87], v[72:75], off
	v_lshlrev_b32_e32 v82, 16, v76
	v_and_b32_e32 v83, 0xffff0000, v76
	v_lshlrev_b32_e32 v76, 16, v77
	v_and_b32_e32 v77, 0xffff0000, v77
	v_lshlrev_b32_e32 v84, 16, v78
	v_and_b32_e32 v85, 0xffff0000, v78
	v_lshlrev_b32_e32 v78, 16, v79
	v_and_b32_e32 v79, 0xffff0000, v79
	v_pk_fma_f32 v[70:71], v[70:71], 0.5, v[76:77] op_sel_hi:[1,0,1]
	v_pk_fma_f32 v[68:69], v[68:69], 0.5, v[82:83] op_sel_hi:[1,0,1]
	v_pk_fma_f32 v[76:77], v[66:67], 0.5, v[78:79] op_sel_hi:[1,0,1]
	v_pk_fma_f32 v[78:79], v[64:65], 0.5, v[84:85] op_sel_hi:[1,0,1]
	v_mul_f32_e32 v64, v69, v69
	v_mul_f32_e32 v65, v71, v71
	v_mul_f32_e32 v66, v79, v79
	v_mul_f32_e32 v67, v77, v77
	v_fmac_f32_e32 v64, v68, v68
	v_fmac_f32_e32 v65, v70, v70
	v_fmac_f32_e32 v66, v78, v78
	v_fmac_f32_e32 v67, v76, v76
	v_add_f32_e32 v64, v64, v65
	v_add_f32_e32 v65, v66, v67
	v_add_f32_e32 v64, v64, v65
	v_add_f32_e32 v64, v88, v64
	ds_bpermute_b32 v65, v114, v64
	v_cvt_pk_bf16_f32 v66, v68, v69
	v_cvt_pk_bf16_f32 v67, v70, v71
	v_cvt_pk_bf16_f32 v68, v78, v79
	v_cvt_pk_bf16_f32 v69, v76, v77
	s_waitcnt lgkmcnt(0)
	v_add_f32_e32 v64, v64, v65
	v_mov_b32_e32 v65, v64
	s_nop 1
	v_permlane32_swap_b32 v64, v65
	global_store_dwordx4 v[86:87], v[66:69], off offset:256
	s_and_saveexec_b64 s[44:45], s[36:37]
	s_cbranch_execz .LBB0_916
	v_lshl_add_u64 v[66:67], v[80:81], 2, s[12:13]
	s_waitcnt lgkmcnt(0)
	v_add_f32_e32 v64, v64, v65
	global_atomic_add_f32 v[66:67], v64, off
.LBB0_916:
	s_or_b64 exec, exec, s[44:45]
	v_add_u32_e32 v64, 0x80, v146
	s_waitcnt lgkmcnt(0)
	v_ashrrev_i32_e32 v65, 31, v64
	v_lshlrev_b64 v[66:67], 11, v[64:65]
	v_lshl_add_u64 v[66:67], s[96:97], 0, v[66:67]
	v_lshl_add_u64 v[70:71], v[144:145], 1, v[66:67]
	s_nop 1
	v_mov_b64_e32 v[66:67], v[196:197]
	v_mov_b64_e32 v[68:69], v[198:199]
	v_lshlrev_b32_e32 v72, 16, v66
	v_and_b32_e32 v73, 0xffff0000, v66
	v_lshlrev_b32_e32 v66, 16, v67
	v_and_b32_e32 v67, 0xffff0000, v67
	v_lshlrev_b32_e32 v74, 16, v68
	v_and_b32_e32 v75, 0xffff0000, v68
	v_lshlrev_b32_e32 v68, 16, v69
	v_and_b32_e32 v69, 0xffff0000, v69
	v_pk_fma_f32 v[66:67], v[62:63], 0.5, v[66:67] op_sel_hi:[1,0,1]
	v_pk_fma_f32 v[72:73], v[60:61], 0.5, v[72:73] op_sel_hi:[1,0,1]
	v_pk_fma_f32 v[68:69], v[58:59], 0.5, v[68:69] op_sel_hi:[1,0,1]
	v_pk_fma_f32 v[74:75], v[56:57], 0.5, v[74:75] op_sel_hi:[1,0,1]
	v_cvt_pk_bf16_f32 v56, v72, v73
	v_cvt_pk_bf16_f32 v57, v66, v67
	v_mul_f32_e32 v73, v73, v73
	v_cvt_pk_bf16_f32 v58, v74, v75
	v_cvt_pk_bf16_f32 v59, v68, v69
	s_nop 1
	v_mov_b64_e32 v[60:61], v[200:201]
	v_mov_b64_e32 v[62:63], v[202:203]
	v_mul_f32_e32 v67, v67, v67
	v_mul_f32_e32 v75, v75, v75
	v_mul_f32_e32 v69, v69, v69
	v_fmac_f32_e32 v73, v72, v72
	v_fmac_f32_e32 v67, v66, v66
	v_fmac_f32_e32 v75, v74, v74
	v_fmac_f32_e32 v69, v68, v68
	v_add_f32_e32 v66, v73, v67
	v_add_f32_e32 v67, v75, v69
	v_add_f32_e32 v72, v66, v67
	global_store_dwordx4 v[70:71], v[56:59], off
	v_lshlrev_b32_e32 v66, 16, v60
	v_and_b32_e32 v67, 0xffff0000, v60
	v_lshlrev_b32_e32 v60, 16, v61
	v_and_b32_e32 v61, 0xffff0000, v61
	v_lshlrev_b32_e32 v68, 16, v62
	v_and_b32_e32 v69, 0xffff0000, v62
	v_lshlrev_b32_e32 v62, 16, v63
	v_and_b32_e32 v63, 0xffff0000, v63
	v_pk_fma_f32 v[54:55], v[54:55], 0.5, v[60:61] op_sel_hi:[1,0,1]
	v_pk_fma_f32 v[52:53], v[52:53], 0.5, v[66:67] op_sel_hi:[1,0,1]
	v_pk_fma_f32 v[60:61], v[50:51], 0.5, v[62:63] op_sel_hi:[1,0,1]
	v_pk_fma_f32 v[62:63], v[48:49], 0.5, v[68:69] op_sel_hi:[1,0,1]
	v_mul_f32_e32 v48, v53, v53
	v_mul_f32_e32 v49, v55, v55
	v_mul_f32_e32 v50, v63, v63
	v_mul_f32_e32 v51, v61, v61
	v_fmac_f32_e32 v48, v52, v52
	v_fmac_f32_e32 v49, v54, v54
	v_fmac_f32_e32 v50, v62, v62
	v_fmac_f32_e32 v51, v60, v60
	v_add_f32_e32 v48, v48, v49
	v_add_f32_e32 v49, v50, v51
	v_add_f32_e32 v48, v48, v49
	v_add_f32_e32 v48, v72, v48
	ds_bpermute_b32 v49, v114, v48
	v_cvt_pk_bf16_f32 v50, v52, v53
	v_cvt_pk_bf16_f32 v51, v54, v55
	v_cvt_pk_bf16_f32 v52, v62, v63
	v_cvt_pk_bf16_f32 v53, v60, v61
	s_waitcnt lgkmcnt(0)
	v_add_f32_e32 v48, v48, v49
	v_mov_b32_e32 v49, v48
	s_nop 1
	v_permlane32_swap_b32 v48, v49
	global_store_dwordx4 v[70:71], v[50:53], off offset:256
	s_and_saveexec_b64 s[44:45], s[36:37]
	s_cbranch_execz .LBB0_918
	v_lshl_add_u64 v[50:51], v[64:65], 2, s[12:13]
	s_waitcnt lgkmcnt(0)
	v_add_f32_e32 v48, v48, v49
	global_atomic_add_f32 v[50:51], v48, off
; __device__ __forceinline__ float sq4(f32x4 a) { return (a.x * a.x + a.y * a.y) + (a.z * a.z + a.w * a.w); }
; __device__ __forceinline__ u32x4 pack8(f32x4 a, f32x4 b) { u32x4 o; o.x = cvt_pk(a.x, a.y); o.y = cvt_pk(a.z, a.w); o.z = cvt_pk(b.x, b.y); o.w = cvt_pk(b.z, b.w); return o; }
; __device__ __forceinline__ void row_stat_add(float* SS, int row, float v, int fq) {
;     v += __shfl_xor(v, 16); v += __shfl_xor(v, 32);
;     if (fq == 0) unsafeAtomicAdd(SS + row, v);
;     __device__ __forceinline__ void operator()(const f32x4 (&acc)[2][2][4][2], const pg8::Unit& u, int wr, int wc, int fr, int fq) const {
;     ...
;         for (int ai = 0; ai < 2; ++ai)
; #pragma unroll
;             for (int m = 0; m < 4; ++m) {
;                 const int row = row0 + ai * 128 + m * 16; float ssq = 0.f;
; #pragma unroll
;                 for (int bj = 0; bj < 2; ++bj) {
;                     const size_t idx = (size_t)row * D + col0 + bj * 128;
;                     f32x4 r0, r1;
;                     if (RF32) { r0 = *(const f32x4*)(R + idx); r1 = *(const f32x4*)(R + idx + 4); }
;                     else { const u32x4 w = *(const u32x4*)(X + idx); r0 = (f32x4){bflo(w.x), bfhi(w.x), bflo(w.y), bfhi(w.y)}; r1 = (f32x4){bflo(w.z), bfhi(w.z), bflo(w.w), bfhi(w.w)}; }
;                     const f32x4 v0 = r0 + acc[ai][bj][m][0] * s, v1 = r1 + acc[ai][bj][m][1] * s;
;                     ssq += sq4(v0) + sq4(v1);
;                     *(u32x4*)(X + idx) = pack8(v0, v1);
;                 }
;                 row_stat_add(SS, row, ssq, fq);
.LBB0_918:
	s_or_b64 exec, exec, s[44:45]
	v_add_u32_e32 v48, 0x90, v146
	s_waitcnt lgkmcnt(0)
	v_ashrrev_i32_e32 v49, 31, v48
	v_lshlrev_b64 v[50:51], 11, v[48:49]
	v_lshl_add_u64 v[50:51], s[96:97], 0, v[50:51]
	v_lshl_add_u64 v[54:55], v[144:145], 1, v[50:51]
	s_nop 1
	v_mov_b64_e32 v[50:51], v[204:205]
	v_mov_b64_e32 v[52:53], v[206:207]
	v_lshlrev_b32_e32 v56, 16, v50
	v_and_b32_e32 v57, 0xffff0000, v50
	v_lshlrev_b32_e32 v50, 16, v51
	v_and_b32_e32 v51, 0xffff0000, v51
	v_lshlrev_b32_e32 v58, 16, v52
	v_and_b32_e32 v59, 0xffff0000, v52
	v_lshlrev_b32_e32 v52, 16, v53
	v_and_b32_e32 v53, 0xffff0000, v53
	v_pk_fma_f32 v[50:51], v[46:47], 0.5, v[50:51] op_sel_hi:[1,0,1]
	v_pk_fma_f32 v[56:57], v[44:45], 0.5, v[56:57] op_sel_hi:[1,0,1]
	v_pk_fma_f32 v[52:53], v[42:43], 0.5, v[52:53] op_sel_hi:[1,0,1]
	v_pk_fma_f32 v[58:59], v[40:41], 0.5, v[58:59] op_sel_hi:[1,0,1]
	v_cvt_pk_bf16_f32 v40, v56, v57
	v_cvt_pk_bf16_f32 v41, v50, v51
	v_mul_f32_e32 v57, v57, v57
	v_cvt_pk_bf16_f32 v42, v58, v59
	v_cvt_pk_bf16_f32 v43, v52, v53
	s_nop 1
	v_mov_b64_e32 v[44:45], v[208:209]
	v_mov_b64_e32 v[46:47], v[210:211]
	v_mul_f32_e32 v51, v51, v51
	v_mul_f32_e32 v59, v59, v59
	v_mul_f32_e32 v53, v53, v53
	v_fmac_f32_e32 v57, v56, v56
	v_fmac_f32_e32 v51, v50, v50
	v_fmac_f32_e32 v59, v58, v58
	v_fmac_f32_e32 v53, v52, v52
	v_add_f32_e32 v50, v57, v51
	v_add_f32_e32 v51, v59, v53
	v_add_f32_e32 v56, v50, v51
	global_store_dwordx4 v[54:55], v[40:43], off
	v_lshlrev_b32_e32 v50, 16, v44
	v_and_b32_e32 v51, 0xffff0000, v44
	v_lshlrev_b32_e32 v44, 16, v45
	v_and_b32_e32 v45, 0xffff0000, v45
	v_lshlrev_b32_e32 v52, 16, v46
	v_and_b32_e32 v53, 0xffff0000, v46
	v_lshlrev_b32_e32 v46, 16, v47
	v_and_b32_e32 v47, 0xffff0000, v47
	v_pk_fma_f32 v[38:39], v[38:39], 0.5, v[44:45] op_sel_hi:[1,0,1]
	v_pk_fma_f32 v[36:37], v[36:37], 0.5, v[50:51] op_sel_hi:[1,0,1]
	v_pk_fma_f32 v[44:45], v[34:35], 0.5, v[46:47] op_sel_hi:[1,0,1]
	v_pk_fma_f32 v[46:47], v[32:33], 0.5, v[52:53] op_sel_hi:[1,0,1]
	v_mul_f32_e32 v32, v37, v37
	v_mul_f32_e32 v33, v39, v39
	v_mul_f32_e32 v34, v47, v47
	v_mul_f32_e32 v35, v45, v45
	v_fmac_f32_e32 v32, v36, v36
	v_fmac_f32_e32 v33, v38, v38
	v_fmac_f32_e32 v34, v46, v46
	v_fmac_f32_e32 v35, v44, v44
	v_add_f32_e32 v32, v32, v33
	v_add_f32_e32 v33, v34, v35
	v_add_f32_e32 v32, v32, v33
	v_add_f32_e32 v32, v56, v32
	ds_bpermute_b32 v33, v114, v32
	v_cvt_pk_bf16_f32 v34, v36, v37
	v_cvt_pk_bf16_f32 v35, v38, v39
	v_cvt_pk_bf16_f32 v36, v46, v47
	v_cvt_pk_bf16_f32 v37, v44, v45
	s_waitcnt lgkmcnt(0)
	v_add_f32_e32 v32, v32, v33
	v_mov_b32_e32 v33, v32
	s_nop 1
	v_permlane32_swap_b32 v32, v33
	global_store_dwordx4 v[54:55], v[34:37], off offset:256
	s_and_saveexec_b64 s[44:45], s[36:37]
	s_cbranch_execz .LBB0_920
	v_lshl_add_u64 v[34:35], v[48:49], 2, s[12:13]
	s_waitcnt lgkmcnt(0)
	v_add_f32_e32 v32, v32, v33
	global_atomic_add_f32 v[34:35], v32, off
; __device__ __forceinline__ float sq4(f32x4 a) { return (a.x * a.x + a.y * a.y) + (a.z * a.z + a.w * a.w); }
; __device__ __forceinline__ u32x4 pack8(f32x4 a, f32x4 b) { u32x4 o; o.x = cvt_pk(a.x, a.y); o.y = cvt_pk(a.z, a.w); o.z = cvt_pk(b.x, b.y); o.w = cvt_pk(b.z, b.w); return o; }
; __device__ __forceinline__ void row_stat_add(float* SS, int row, float v, int fq) {
;     v += __shfl_xor(v, 16); v += __shfl_xor(v, 32);
;     if (fq == 0) unsafeAtomicAdd(SS + row, v);
;     __device__ __forceinline__ void operator()(const f32x4 (&acc)[2][2][4][2], const pg8::Unit& u, int wr, int wc, int fr, int fq) const {
;     ...
;         for (int ai = 0; ai < 2; ++ai)
; #pragma unroll
;             for (int m = 0; m < 4; ++m) {
;                 const int row = row0 + ai * 128 + m * 16; float ssq = 0.f;
; #pragma unroll
;                 for (int bj = 0; bj < 2; ++bj) {
;                     const size_t idx = (size_t)row * D + col0 + bj * 128;
;                     f32x4 r0, r1;
;                     if (RF32) { r0 = *(const f32x4*)(R + idx); r1 = *(const f32x4*)(R + idx + 4); }
;                     else { const u32x4 w = *(const u32x4*)(X + idx); r0 = (f32x4){bflo(w.x), bfhi(w.x), bflo(w.y), bfhi(w.y)}; r1 = (f32x4){bflo(w.z), bfhi(w.z), bflo(w.w), bfhi(w.w)}; }
;                     const f32x4 v0 = r0 + acc[ai][bj][m][0] * s, v1 = r1 + acc[ai][bj][m][1] * s;
;                     ssq += sq4(v0) + sq4(v1);
;                     *(u32x4*)(X + idx) = pack8(v0, v1);
;                 }
;                 row_stat_add(SS, row, ssq, fq);
.LBB0_920:
	s_or_b64 exec, exec, s[44:45]
	v_add_u32_e32 v32, 0xa0, v146
	s_waitcnt lgkmcnt(0)
	v_ashrrev_i32_e32 v33, 31, v32
	v_lshlrev_b64 v[34:35], 11, v[32:33]
	v_lshl_add_u64 v[34:35], s[96:97], 0, v[34:35]
	v_lshl_add_u64 v[38:39], v[144:145], 1, v[34:35]
	s_nop 1
	v_mov_b64_e32 v[34:35], v[212:213]
	v_mov_b64_e32 v[36:37], v[214:215]
	v_lshlrev_b32_e32 v40, 16, v34
	v_and_b32_e32 v41, 0xffff0000, v34
	v_lshlrev_b32_e32 v34, 16, v35
	v_and_b32_e32 v35, 0xffff0000, v35
	v_lshlrev_b32_e32 v42, 16, v36
	v_and_b32_e32 v43, 0xffff0000, v36
	v_lshlrev_b32_e32 v36, 16, v37
	v_and_b32_e32 v37, 0xffff0000, v37
	v_pk_fma_f32 v[34:35], v[30:31], 0.5, v[34:35] op_sel_hi:[1,0,1]
	v_pk_fma_f32 v[40:41], v[28:29], 0.5, v[40:41] op_sel_hi:[1,0,1]
	v_pk_fma_f32 v[36:37], v[26:27], 0.5, v[36:37] op_sel_hi:[1,0,1]
	v_pk_fma_f32 v[42:43], v[24:25], 0.5, v[42:43] op_sel_hi:[1,0,1]
	v_cvt_pk_bf16_f32 v24, v40, v41
	v_cvt_pk_bf16_f32 v25, v34, v35
	v_mul_f32_e32 v41, v41, v41
	v_cvt_pk_bf16_f32 v26, v42, v43
	v_cvt_pk_bf16_f32 v27, v36, v37
	s_nop 1
	v_mov_b64_e32 v[28:29], v[216:217]
	v_mov_b64_e32 v[30:31], v[218:219]
	v_mul_f32_e32 v35, v35, v35
	v_mul_f32_e32 v43, v43, v43
	v_mul_f32_e32 v37, v37, v37
	v_fmac_f32_e32 v41, v40, v40
	v_fmac_f32_e32 v35, v34, v34
	v_fmac_f32_e32 v43, v42, v42
	v_fmac_f32_e32 v37, v36, v36
	v_add_f32_e32 v34, v41, v35
	v_add_f32_e32 v35, v43, v37
	v_add_f32_e32 v40, v34, v35
	global_store_dwordx4 v[38:39], v[24:27], off
	v_lshlrev_b32_e32 v34, 16, v28
	v_and_b32_e32 v35, 0xffff0000, v28
	v_lshlrev_b32_e32 v28, 16, v29
	v_and_b32_e32 v29, 0xffff0000, v29
	v_lshlrev_b32_e32 v36, 16, v30
	v_and_b32_e32 v37, 0xffff0000, v30
	v_lshlrev_b32_e32 v30, 16, v31
	v_and_b32_e32 v31, 0xffff0000, v31
	v_pk_fma_f32 v[22:23], v[22:23], 0.5, v[28:29] op_sel_hi:[1,0,1]
	v_pk_fma_f32 v[20:21], v[20:21], 0.5, v[34:35] op_sel_hi:[1,0,1]
	v_pk_fma_f32 v[28:29], v[18:19], 0.5, v[30:31] op_sel_hi:[1,0,1]
	v_pk_fma_f32 v[30:31], v[16:17], 0.5, v[36:37] op_sel_hi:[1,0,1]
	v_mul_f32_e32 v16, v21, v21
	v_mul_f32_e32 v17, v23, v23
	v_mul_f32_e32 v18, v31, v31
	v_mul_f32_e32 v19, v29, v29
	v_fmac_f32_e32 v16, v20, v20
	v_fmac_f32_e32 v17, v22, v22
	v_fmac_f32_e32 v18, v30, v30
	v_fmac_f32_e32 v19, v28, v28
	v_add_f32_e32 v16, v16, v17
	v_add_f32_e32 v17, v18, v19
	v_add_f32_e32 v16, v16, v17
	v_add_f32_e32 v16, v40, v16
	ds_bpermute_b32 v17, v114, v16
	v_cvt_pk_bf16_f32 v18, v20, v21
	v_cvt_pk_bf16_f32 v19, v22, v23
	v_cvt_pk_bf16_f32 v20, v30, v31
	v_cvt_pk_bf16_f32 v21, v28, v29
	s_waitcnt lgkmcnt(0)
	v_add_f32_e32 v16, v16, v17
	v_mov_b32_e32 v17, v16
	s_nop 1
	v_permlane32_swap_b32 v16, v17
	global_store_dwordx4 v[38:39], v[18:21], off offset:256
	s_and_saveexec_b64 s[44:45], s[36:37]
	s_cbranch_execz .LBB0_922
	v_lshl_add_u64 v[18:19], v[32:33], 2, s[12:13]
	s_waitcnt lgkmcnt(0)
	v_add_f32_e32 v16, v16, v17
	global_atomic_add_f32 v[18:19], v16, off
.LBB0_922:
	s_or_b64 exec, exec, s[44:45]
	v_add_u32_e32 v16, 0xb0, v146
	s_waitcnt lgkmcnt(0)
	v_ashrrev_i32_e32 v17, 31, v16
	v_lshlrev_b64 v[18:19], 11, v[16:17]
	v_lshl_add_u64 v[18:19], s[96:97], 0, v[18:19]
	v_lshl_add_u64 v[22:23], v[144:145], 1, v[18:19]
	s_nop 1
	v_mov_b64_e32 v[18:19], v[220:221]
	v_mov_b64_e32 v[20:21], v[222:223]
	v_lshlrev_b32_e32 v24, 16, v18
	v_and_b32_e32 v25, 0xffff0000, v18
	v_lshlrev_b32_e32 v18, 16, v19
	v_and_b32_e32 v19, 0xffff0000, v19
	v_lshlrev_b32_e32 v26, 16, v20
	v_and_b32_e32 v27, 0xffff0000, v20
	v_lshlrev_b32_e32 v20, 16, v21
	v_and_b32_e32 v21, 0xffff0000, v21
	v_pk_fma_f32 v[18:19], v[14:15], 0.5, v[18:19] op_sel_hi:[1,0,1]
	v_pk_fma_f32 v[24:25], v[12:13], 0.5, v[24:25] op_sel_hi:[1,0,1]
	v_pk_fma_f32 v[20:21], v[10:11], 0.5, v[20:21] op_sel_hi:[1,0,1]
	v_pk_fma_f32 v[26:27], v[8:9], 0.5, v[26:27] op_sel_hi:[1,0,1]
	v_cvt_pk_bf16_f32 v8, v24, v25
	v_cvt_pk_bf16_f32 v9, v18, v19
	v_mul_f32_e32 v25, v25, v25
	v_cvt_pk_bf16_f32 v10, v26, v27
	v_cvt_pk_bf16_f32 v11, v20, v21
	global_load_dwordx4 v[12:15], v[22:23], off offset:256
	v_mul_f32_e32 v19, v19, v19
	v_mul_f32_e32 v27, v27, v27
	v_mul_f32_e32 v21, v21, v21
	v_fmac_f32_e32 v25, v24, v24
	v_fmac_f32_e32 v19, v18, v18
	v_fmac_f32_e32 v27, v26, v26
	v_fmac_f32_e32 v21, v20, v20
	v_add_f32_e32 v18, v25, v19
	v_add_f32_e32 v19, v27, v21
	v_add_f32_e32 v24, v18, v19
	global_store_dwordx4 v[22:23], v[8:11], off
	s_waitcnt vmcnt(1)
	v_lshlrev_b32_e32 v18, 16, v12
	v_and_b32_e32 v19, 0xffff0000, v12
	v_lshlrev_b32_e32 v12, 16, v13
	v_and_b32_e32 v13, 0xffff0000, v13
	v_lshlrev_b32_e32 v20, 16, v14
	v_and_b32_e32 v21, 0xffff0000, v14
	v_lshlrev_b32_e32 v14, 16, v15
	v_and_b32_e32 v15, 0xffff0000, v15
	v_pk_fma_f32 v[6:7], v[6:7], 0.5, v[12:13] op_sel_hi:[1,0,1]
	v_pk_fma_f32 v[4:5], v[4:5], 0.5, v[18:19] op_sel_hi:[1,0,1]
	v_pk_fma_f32 v[12:13], v[2:3], 0.5, v[14:15] op_sel_hi:[1,0,1]
	v_pk_fma_f32 v[14:15], v[0:1], 0.5, v[20:21] op_sel_hi:[1,0,1]
	v_mul_f32_e32 v0, v5, v5
	v_mul_f32_e32 v1, v7, v7
	v_mul_f32_e32 v2, v15, v15
	v_mul_f32_e32 v3, v13, v13
	v_fmac_f32_e32 v0, v4, v4
	v_fmac_f32_e32 v1, v6, v6
	v_fmac_f32_e32 v2, v14, v14
	v_fmac_f32_e32 v3, v12, v12
	v_add_f32_e32 v0, v0, v1
	v_add_f32_e32 v1, v2, v3
	v_add_f32_e32 v0, v0, v1
	v_add_f32_e32 v0, v24, v0
	ds_bpermute_b32 v1, v114, v0
	v_cvt_pk_bf16_f32 v2, v4, v5
	v_cvt_pk_bf16_f32 v3, v6, v7
	v_cvt_pk_bf16_f32 v4, v14, v15
	v_cvt_pk_bf16_f32 v5, v12, v13
	s_waitcnt lgkmcnt(0)
	v_add_f32_e32 v0, v0, v1
	v_mov_b32_e32 v1, v0
	s_nop 1
	v_permlane32_swap_b32 v0, v1
	global_store_dwordx4 v[22:23], v[2:5], off offset:256
	s_and_saveexec_b64 s[44:45], s[36:37]
	s_cbranch_execz .LBB0_924
	v_lshl_add_u64 v[2:3], v[16:17], 2, s[12:13]
	s_waitcnt lgkmcnt(0)
	v_add_f32_e32 v0, v0, v1
	global_atomic_add_f32 v[2:3], v0, off
